# row phases: wave-wide sum via DPP + permlane16/32 swap instead of six ds_bpermute round trips
# baseline (speedup 1.0000x reference)
.LBB0_160:
	global_load_dwordx4 v[30:33], v[22:23], off offset:-3072 nt
	global_load_dwordx4 v[34:37], v[22:23], off offset:-2048 nt
	global_load_dwordx4 v[38:41], v[22:23], off offset:-1024 nt
	global_load_dwordx4 v[42:45], v[22:23], off nt
	s_add_i32 s12, s12, s34
	v_lshl_add_u64 v[22:23], v[22:23], 0, s[14:15]
	s_cmp_lt_i32 s12, 0x10000
	s_waitcnt vmcnt(3)
	v_pk_mul_f32 v[46:47], v[32:33], v[32:33]
	v_pk_mul_f32 v[48:49], v[30:31], v[30:31]
	s_waitcnt vmcnt(2)
	v_pk_mul_f32 v[50:51], v[36:37], v[36:37]
	v_pk_mul_f32 v[52:53], v[34:35], v[34:35]
	v_pk_mov_b32 v[58:59], v[48:49], v[46:47] op_sel:[1,0]
	v_mov_b32_e32 v49, v47
	v_pk_mov_b32 v[46:47], v[52:53], v[50:51] op_sel:[1,0]
	v_mov_b32_e32 v53, v51
	s_waitcnt vmcnt(0)
	v_mul_f32_e32 v57, v42, v42
	v_mul_f32_e32 v54, v39, v39
	v_mul_f32_e32 v56, v41, v41
	v_pk_add_f32 v[48:49], v[58:59], v[48:49]
	v_pk_add_f32 v[46:47], v[46:47], v[52:53]
	v_mul_f32_e32 v60, v43, v43
	v_mul_f32_e32 v61, v44, v44
	v_mul_f32_e32 v62, v45, v45
	v_pk_fma_f32 v[50:51], v[38:39], v[38:39], v[54:55] op_sel_hi:[1,1,0]
	v_pk_fma_f32 v[54:55], v[40:41], v[40:41], v[56:57] op_sel_hi:[1,1,0]
	v_pk_add_f32 v[48:49], v[48:49], v[48:49] op_sel:[0,1] op_sel_hi:[1,0]
	v_pk_add_f32 v[46:47], v[46:47], v[46:47] op_sel:[0,1] op_sel_hi:[1,0]
	v_mov_b32_e32 v51, v61
	v_mov_b32_e32 v55, v62
	v_mov_b32_e32 v49, v57
	v_mov_b32_e32 v47, v60
	v_pk_add_f32 v[50:51], v[50:51], v[54:55]
	v_pk_add_f32 v[46:47], v[48:49], v[46:47]
	s_nop 0
	v_pk_add_f32 v[46:47], v[46:47], v[50:51]
	s_nop 0
	v_add_f32_e32 v46, v46, v47
	s_nop 1
	v_add_f32_dpp v46, v46, v46 quad_perm:[1,0,3,2] row_mask:0xf bank_mask:0xf bound_ctrl:1
	s_nop 1
	v_add_f32_dpp v46, v46, v46 quad_perm:[2,3,0,1] row_mask:0xf bank_mask:0xf bound_ctrl:1
	s_nop 1
	v_add_f32_dpp v46, v46, v46 row_half_mirror row_mask:0xf bank_mask:0xf bound_ctrl:1
	s_nop 1
	v_add_f32_dpp v46, v46, v46 row_ror:8 row_mask:0xf bank_mask:0xf bound_ctrl:1
	v_mov_b32_e32 v47, v46
	s_nop 1
	v_permlane16_swap_b32 v47, v46
	s_nop 1
	v_add_f32_e32 v46, v46, v47
	v_mov_b32_e32 v47, v46
	s_nop 1
	v_permlane32_swap_b32 v47, v46
	s_nop 1
	v_add_f32_e32 v46, v46, v47
	v_fmamk_f32 v46, v46, 0x3a800000, v29
	v_rsq_f32_e32 v46, v46
	s_nop 0
	v_pk_mul_f32 v[30:31], v[30:31], v[46:47] op_sel_hi:[1,0]
	v_pk_mul_f32 v[32:33], v[32:33], v[46:47] op_sel_hi:[1,0]
	v_pk_mul_f32 v[34:35], v[34:35], v[46:47] op_sel_hi:[1,0]
	v_pk_mul_f32 v[36:37], v[36:37], v[46:47] op_sel_hi:[1,0]
	v_pk_mul_f32 v[38:39], v[38:39], v[46:47] op_sel_hi:[1,0]
	v_pk_mul_f32 v[40:41], v[40:41], v[46:47] op_sel_hi:[1,0]
	v_pk_mul_f32 v[42:43], v[42:43], v[46:47] op_sel_hi:[1,0]
	v_pk_mul_f32 v[44:45], v[44:45], v[46:47] op_sel_hi:[1,0]
	v_pk_mul_f32 v[32:33], v[4:5], v[32:33]
	v_pk_mul_f32 v[30:31], v[2:3], v[30:31]
	v_pk_mul_f32 v[36:37], v[8:9], v[36:37]
	v_pk_mul_f32 v[34:35], v[6:7], v[34:35]
	v_pk_mul_f32 v[40:41], v[12:13], v[40:41]
	v_pk_mul_f32 v[38:39], v[10:11], v[38:39]
	v_pk_mul_f32 v[44:45], v[16:17], v[44:45]
	v_pk_mul_f32 v[42:43], v[14:15], v[42:43]
	v_cvt_pk_bf16_f32 v30, v30, v31
	v_cvt_pk_bf16_f32 v31, v32, v33
	v_cvt_pk_bf16_f32 v32, v34, v35
	v_cvt_pk_bf16_f32 v33, v36, v37
	v_cvt_pk_bf16_f32 v34, v38, v39
	v_cvt_pk_bf16_f32 v35, v40, v41
	v_cvt_pk_bf16_f32 v36, v42, v43
	v_cvt_pk_bf16_f32 v37, v44, v45
	global_store_dwordx2 v[20:21], v[30:31], off
	global_store_dwordx2 v[20:21], v[32:33], off offset:512
	global_store_dwordx2 v[20:21], v[34:35], off offset:1024
	global_store_dwordx2 v[20:21], v[36:37], off offset:1536
	v_lshl_add_u64 v[20:21], v[20:21], 0, s[4:5]
	s_cbranch_scc1 .LBB0_160

.LBB0_1181:
	v_pk_mul_f32 v[60:61], v[46:47], v[46:47]
	v_pk_mul_f32 v[62:63], v[44:45], v[44:45]
	s_add_i32 s8, s8, s34
	v_pk_mov_b32 v[64:65], v[62:63], v[60:61] op_sel:[1,0]
	v_mov_b32_e32 v63, v61
	v_pk_add_f32 v[60:61], v[64:65], v[62:63]
	v_pk_mul_f32 v[62:63], v[42:43], v[42:43]
	v_pk_add_f32 v[60:61], v[60:61], v[60:61] op_sel_hi:[0,1]
	v_pk_mul_f32 v[64:65], v[40:41], v[40:41]
	v_mul_f32_e32 v60, v36, v36
	v_pk_mov_b32 v[66:67], v[64:65], v[62:63] op_sel:[1,0]
	v_mov_b32_e32 v65, v63
	v_pk_add_f32 v[62:63], v[66:67], v[64:65]
	v_pk_fma_f32 v[64:65], v[36:37], v[36:37], v[60:61] op_sel_hi:[1,1,0]
	v_mul_f32_e32 v60, v38, v38
	v_pk_add_f32 v[62:63], v[62:63], v[62:63] op_sel_hi:[0,1]
	v_pk_fma_f32 v[66:67], v[38:39], v[38:39], v[60:61] op_sel_hi:[1,1,0]
	v_mul_f32_e32 v64, v32, v32
	v_mul_f32_e32 v66, v33, v33
	v_mul_f32_e32 v60, v34, v34
	v_mul_f32_e32 v62, v35, v35
	v_pk_add_f32 v[64:65], v[64:65], v[66:67]
	v_pk_add_f32 v[60:61], v[60:61], v[62:63]
	s_add_u32 s12, s12, s14
	v_pk_add_f32 v[60:61], v[64:65], v[60:61]
	s_addc_u32 s13, s13, s15
	v_add_f32_e32 v59, v60, v61
	s_nop 1
	v_add_f32_dpp v59, v59, v59 quad_perm:[1,0,3,2] row_mask:0xf bank_mask:0xf bound_ctrl:1
	s_add_u32 s4, s4, s14
	v_add_co_u32_e32 v62, vcc, s0, v50
	s_addc_u32 s5, s5, s15
	s_nop 1
	v_add_f32_dpp v59, v59, v59 quad_perm:[2,3,0,1] row_mask:0xf bank_mask:0xf bound_ctrl:1
	v_addc_co_u32_e32 v63, vcc, -1, v51, vcc
	s_cmp_lt_i32 s8, 0x10000
	v_lshl_add_u64 v[50:51], v[50:51], 0, s[6:7]
	s_nop 1
	v_add_f32_dpp v59, v59, v59 row_half_mirror row_mask:0xf bank_mask:0xf bound_ctrl:1
	s_nop 1
	v_add_f32_dpp v59, v59, v59 row_ror:8 row_mask:0xf bank_mask:0xf bound_ctrl:1
	v_mov_b32_e32 v60, v59
	s_nop 1
	v_permlane16_swap_b32 v60, v59
	s_nop 1
	v_add_f32_e32 v59, v59, v60
	v_mov_b32_e32 v60, v59
	s_nop 1
	v_permlane32_swap_b32 v60, v59
	s_nop 1
	v_add_f32_e32 v59, v59, v60
	v_fmamk_f32 v59, v59, 0x3a800000, v58
	v_rsq_f32_e32 v60, v59
	s_nop 0
	v_pk_mul_f32 v[44:45], v[44:45], v[60:61] op_sel_hi:[1,0]
	v_pk_mul_f32 v[46:47], v[46:47], v[60:61] op_sel_hi:[1,0]
	v_pk_mul_f32 v[40:41], v[40:41], v[60:61] op_sel_hi:[1,0]
	v_pk_mul_f32 v[42:43], v[42:43], v[60:61] op_sel_hi:[1,0]
	v_pk_mul_f32 v[36:37], v[36:37], v[60:61] op_sel_hi:[1,0]
	v_pk_mul_f32 v[38:39], v[38:39], v[60:61] op_sel_hi:[1,0]
	v_pk_mul_f32 v[32:33], v[32:33], v[60:61] op_sel_hi:[1,0]
	v_pk_mul_f32 v[34:35], v[34:35], v[60:61] op_sel_hi:[1,0]
	v_pk_mul_f32 v[46:47], v[10:11], v[46:47]
	v_pk_mul_f32 v[44:45], v[8:9], v[44:45]
	v_pk_mul_f32 v[42:43], v[14:15], v[42:43]
	v_pk_mul_f32 v[40:41], v[12:13], v[40:41]
	v_pk_mul_f32 v[38:39], v[26:27], v[38:39]
	v_pk_mul_f32 v[36:37], v[24:25], v[36:37]
	v_pk_mul_f32 v[34:35], v[30:31], v[34:35]
	v_pk_mul_f32 v[32:33], v[28:29], v[32:33]
	v_cvt_pk_bf16_f32 v44, v44, v45
	v_cvt_pk_bf16_f32 v45, v46, v47
	v_cvt_pk_bf16_f32 v40, v40, v41
	v_cvt_pk_bf16_f32 v41, v42, v43
	v_cvt_pk_bf16_f32 v36, v36, v37
	v_cvt_pk_bf16_f32 v37, v38, v39
	v_cvt_pk_bf16_f32 v32, v32, v33
	v_cvt_pk_bf16_f32 v33, v34, v35
	global_store_dwordx2 v[62:63], v[44:45], off offset:-1536
	global_store_dwordx2 v[62:63], v[40:41], off offset:-1024
	global_store_dwordx2 v[62:63], v[36:37], off offset:-512
	global_store_dwordx2 v[62:63], v[32:33], off
	s_cbranch_scc0 .LBB0_1184
.LBB0_1182:
	global_load_dwordx2 v[40:41], v[50:51], off offset:-1536 nt
	global_load_dwordx2 v[42:43], v[50:51], off offset:-1024 nt
	global_load_dwordx2 v[44:45], v[50:51], off offset:-512 nt
	global_load_dwordx2 v[46:47], v[50:51], off nt
	v_lshl_add_u64 v[68:69], s[12:13], 0, v[48:49]
	global_load_dwordx4 v[32:35], v[68:69], off nt
	global_load_dwordx4 v[36:39], v[68:69], off offset:1024 nt
	global_load_dwordx4 v[60:63], v[68:69], off offset:2048 nt
	global_load_dwordx4 v[64:67], v[68:69], off offset:3072 nt
	s_andn2_b64 vcc, exec, s[10:11]
	s_waitcnt vmcnt(7)
	v_lshlrev_b32_e32 v68, 16, v40
	v_and_b32_e32 v69, 0xffff0000, v40
	v_lshlrev_b32_e32 v40, 16, v41
	v_and_b32_e32 v41, 0xffff0000, v41
	s_waitcnt vmcnt(6)
	v_lshlrev_b32_e32 v71, 16, v43
	v_lshlrev_b32_e32 v70, 16, v42
	v_and_b32_e32 v43, 0xffff0000, v43
	v_and_b32_e32 v42, 0xffff0000, v42
	s_waitcnt vmcnt(5)
	v_and_b32_e32 v73, 0xffff0000, v44
	s_waitcnt vmcnt(4)
	v_lshlrev_b32_e32 v75, 16, v46
	v_and_b32_e32 v77, 0xffff0000, v46
	v_mul_f32_e32 v74, v41, v41
	v_mul_f32_e32 v76, v69, v69
	v_lshlrev_b32_e32 v72, 16, v44
	v_lshlrev_b32_e32 v44, 16, v45
	v_and_b32_e32 v45, 0xffff0000, v45
	v_pk_mul_f32 v[78:79], v[42:43], v[42:43]
	v_mov_b32_e32 v81, v75
	v_mul_f32_e32 v80, v73, v73
	v_pk_fma_f32 v[84:85], v[40:41], v[40:41], v[74:75] op_sel_hi:[1,1,0]
	v_pk_fma_f32 v[86:87], v[68:69], v[68:69], v[76:77] op_sel_hi:[1,1,0]
	v_lshlrev_b32_e32 v46, 16, v47
	v_and_b32_e32 v47, 0xffff0000, v47
	v_mul_f32_e32 v82, v45, v45
	v_pk_fma_f32 v[78:79], v[70:71], v[70:71], v[78:79]
	v_pk_fma_f32 v[88:89], v[72:73], v[72:73], v[80:81] op_sel_hi:[1,1,0]
	v_mov_b32_e32 v74, v86
	v_mov_b32_e32 v80, v84
	v_mul_f32_e32 v59, v77, v77
	v_mul_f32_e32 v90, v46, v46
	v_mul_f32_e32 v91, v47, v47
	v_pk_fma_f32 v[82:83], v[44:45], v[44:45], v[82:83] op_sel_hi:[1,1,0]
	v_pk_add_f32 v[84:85], v[86:87], v[84:85]
	v_pk_add_f32 v[78:79], v[78:79], v[78:79] op_sel:[0,1] op_sel_hi:[1,0]
	v_pk_mul_f32 v[80:81], v[74:75], v[80:81]
	v_mov_b32_e32 v89, v90
	v_mov_b32_e32 v83, v91
	v_mov_b32_e32 v79, v59
	v_mov_b32_e32 v85, v81
	v_pk_add_f32 v[82:83], v[88:89], v[82:83]
	v_pk_add_f32 v[78:79], v[84:85], v[78:79]
	v_mov_b32_e32 v76, v75
	v_pk_add_f32 v[78:79], v[78:79], v[82:83]
	s_nop 0
	v_add_f32_e32 v59, v78, v79
	s_nop 1
	v_add_f32_dpp v59, v59, v59 quad_perm:[1,0,3,2] row_mask:0xf bank_mask:0xf bound_ctrl:1
	v_mov_b32_e32 v78, v70
	v_mov_b32_e32 v79, v42
	v_mov_b32_e32 v42, v71
	s_nop 1
	v_add_f32_dpp v59, v59, v59 quad_perm:[2,3,0,1] row_mask:0xf bank_mask:0xf bound_ctrl:1
	s_nop 1
	v_add_f32_dpp v59, v59, v59 row_half_mirror row_mask:0xf bank_mask:0xf bound_ctrl:1
	s_nop 1
	v_add_f32_dpp v59, v59, v59 row_ror:8 row_mask:0xf bank_mask:0xf bound_ctrl:1
	v_mov_b32_e32 v74, v59
	s_nop 1
	v_permlane16_swap_b32 v74, v59
	s_nop 1
	v_add_f32_e32 v59, v59, v74
	v_mov_b32_e32 v74, v59
	s_nop 1
	v_permlane32_swap_b32 v74, v59
	s_nop 1
	v_add_f32_e32 v59, v59, v74
	v_fmamk_f32 v59, v59, 0x3a800000, v58
	v_rsq_f32_e32 v70, v59
	s_nop 0
	v_pk_mul_f32 v[68:69], v[70:71], v[68:69] op_sel_hi:[0,1]
	v_pk_mul_f32 v[40:41], v[70:71], v[40:41] op_sel_hi:[0,1]
	v_pk_mul_f32 v[74:75], v[70:71], v[78:79] op_sel_hi:[0,1]
	v_pk_mul_f32 v[42:43], v[70:71], v[42:43] op_sel_hi:[0,1]
	v_pk_mul_f32 v[72:73], v[70:71], v[72:73] op_sel_hi:[0,1]
	v_pk_mul_f32 v[78:79], v[70:71], v[44:45] op_sel_hi:[0,1]
	v_pk_mul_f32 v[76:77], v[76:77], v[70:71] op_sel_hi:[1,0]
	v_pk_mul_f32 v[70:71], v[46:47], v[70:71] op_sel_hi:[1,0]
	s_waitcnt vmcnt(3)
	v_pk_fma_f32 v[46:47], v[2:3], v[40:41], v[34:35]
	v_pk_fma_f32 v[44:45], v[0:1], v[68:69], v[32:33]
	s_waitcnt vmcnt(2)
	v_pk_fma_f32 v[42:43], v[6:7], v[42:43], v[38:39]
	v_pk_fma_f32 v[40:41], v[4:5], v[74:75], v[36:37]
	s_waitcnt vmcnt(1)
	v_pk_fma_f32 v[38:39], v[18:19], v[78:79], v[62:63]
	v_pk_fma_f32 v[36:37], v[16:17], v[72:73], v[60:61]
	s_waitcnt vmcnt(0)
	v_pk_fma_f32 v[34:35], v[22:23], v[70:71], v[66:67]
	v_pk_fma_f32 v[32:33], v[20:21], v[76:77], v[64:65]
	s_cbranch_vccnz .LBB0_1181
	v_lshl_add_u64 v[60:61], s[4:5], 0, v[48:49]
	global_store_dwordx4 v[60:61], v[44:47], off nt
	global_store_dwordx4 v[60:61], v[40:43], off offset:1024 nt
	global_store_dwordx4 v[60:61], v[36:39], off offset:2048 nt
	global_store_dwordx4 v[60:61], v[32:35], off offset:3072 nt
	s_branch .LBB0_1181

.LBB0_1432:
	v_pk_mul_f32 v[60:61], v[46:47], v[46:47]
	v_pk_mul_f32 v[62:63], v[44:45], v[44:45]
	s_add_i32 s3, s3, s34
	v_pk_mov_b32 v[64:65], v[62:63], v[60:61] op_sel:[1,0]
	v_mov_b32_e32 v63, v61
	v_pk_add_f32 v[60:61], v[64:65], v[62:63]
	v_pk_mul_f32 v[62:63], v[42:43], v[42:43]
	v_pk_add_f32 v[60:61], v[60:61], v[60:61] op_sel_hi:[0,1]
	v_pk_mul_f32 v[64:65], v[40:41], v[40:41]
	v_mul_f32_e32 v60, v36, v36
	v_pk_mov_b32 v[66:67], v[64:65], v[62:63] op_sel:[1,0]
	v_mov_b32_e32 v65, v63
	v_pk_add_f32 v[62:63], v[66:67], v[64:65]
	v_pk_fma_f32 v[64:65], v[36:37], v[36:37], v[60:61] op_sel_hi:[1,1,0]
	v_mul_f32_e32 v60, v38, v38
	v_pk_add_f32 v[62:63], v[62:63], v[62:63] op_sel_hi:[0,1]
	v_pk_fma_f32 v[66:67], v[38:39], v[38:39], v[60:61] op_sel_hi:[1,1,0]
	v_mul_f32_e32 v64, v32, v32
	v_mul_f32_e32 v66, v33, v33
	v_mul_f32_e32 v60, v34, v34
	v_mul_f32_e32 v62, v35, v35
	v_pk_add_f32 v[64:65], v[64:65], v[66:67]
	v_pk_add_f32 v[60:61], v[60:61], v[62:63]
	v_add_co_u32_e32 v62, vcc, s1, v48
	v_pk_add_f32 v[60:61], v[64:65], v[60:61]
	s_nop 0
	v_addc_co_u32_e32 v63, vcc, -1, v49, vcc
	v_add_f32_e32 v60, v60, v61
	s_nop 1
	v_add_f32_dpp v60, v60, v60 quad_perm:[1,0,3,2] row_mask:0xf bank_mask:0xf bound_ctrl:1
	v_lshl_add_u64 v[48:49], v[48:49], 0, s[16:17]
	s_cmp_lt_i32 s3, 0x10000
	v_lshl_add_u64 v[50:51], v[50:51], 0, s[18:19]
	s_nop 1
	v_add_f32_dpp v60, v60, v60 quad_perm:[2,3,0,1] row_mask:0xf bank_mask:0xf bound_ctrl:1
	s_nop 1
	v_add_f32_dpp v60, v60, v60 row_half_mirror row_mask:0xf bank_mask:0xf bound_ctrl:1
	s_nop 1
	v_add_f32_dpp v60, v60, v60 row_ror:8 row_mask:0xf bank_mask:0xf bound_ctrl:1
	v_mov_b32_e32 v61, v60
	s_nop 1
	v_permlane16_swap_b32 v61, v60
	s_nop 1
	v_add_f32_e32 v60, v60, v61
	v_mov_b32_e32 v61, v60
	s_nop 1
	v_permlane32_swap_b32 v61, v60
	s_nop 1
	v_add_f32_e32 v60, v60, v61
	v_fmamk_f32 v60, v60, 0x3a800000, v59
	v_rsq_f32_e32 v60, v60
	s_nop 0
	v_pk_mul_f32 v[44:45], v[44:45], v[60:61] op_sel_hi:[1,0]
	v_pk_mul_f32 v[46:47], v[46:47], v[60:61] op_sel_hi:[1,0]
	v_pk_mul_f32 v[40:41], v[40:41], v[60:61] op_sel_hi:[1,0]
	v_pk_mul_f32 v[42:43], v[42:43], v[60:61] op_sel_hi:[1,0]
	v_pk_mul_f32 v[36:37], v[36:37], v[60:61] op_sel_hi:[1,0]
	v_pk_mul_f32 v[38:39], v[38:39], v[60:61] op_sel_hi:[1,0]
	v_pk_mul_f32 v[32:33], v[32:33], v[60:61] op_sel_hi:[1,0]
	v_pk_mul_f32 v[34:35], v[34:35], v[60:61] op_sel_hi:[1,0]
	v_pk_mul_f32 v[46:47], v[26:27], v[46:47]
	v_pk_mul_f32 v[44:45], v[24:25], v[44:45]
	v_pk_mul_f32 v[42:43], v[10:11], v[42:43]
	v_pk_mul_f32 v[40:41], v[8:9], v[40:41]
	v_pk_mul_f32 v[38:39], v[14:15], v[38:39]
	v_pk_mul_f32 v[36:37], v[12:13], v[36:37]
	v_pk_mul_f32 v[34:35], v[30:31], v[34:35]
	v_pk_mul_f32 v[32:33], v[28:29], v[32:33]
	v_cvt_pk_bf16_f32 v44, v44, v45
	v_cvt_pk_bf16_f32 v45, v46, v47
	v_cvt_pk_bf16_f32 v40, v40, v41
	v_cvt_pk_bf16_f32 v41, v42, v43
	v_cvt_pk_bf16_f32 v36, v36, v37
	v_cvt_pk_bf16_f32 v37, v38, v39
	v_cvt_pk_bf16_f32 v32, v32, v33
	v_cvt_pk_bf16_f32 v33, v34, v35
	global_store_dwordx2 v[62:63], v[44:45], off offset:-1536
	global_store_dwordx2 v[62:63], v[40:41], off offset:-1024
	global_store_dwordx2 v[62:63], v[36:37], off offset:-512
	global_store_dwordx2 v[62:63], v[32:33], off
	s_cbranch_scc0 .LBB0_1435
.LBB0_1433:
	global_load_dwordx2 v[40:41], v[48:49], off offset:-1536 nt
	global_load_dwordx2 v[42:43], v[48:49], off offset:-1024 nt
	global_load_dwordx2 v[44:45], v[48:49], off offset:-512 nt
	global_load_dwordx2 v[46:47], v[48:49], off nt
	global_load_dwordx4 v[32:35], v[50:51], off offset:-3072 nt
	global_load_dwordx4 v[36:39], v[50:51], off offset:-2048 nt
	global_load_dwordx4 v[60:63], v[50:51], off offset:-1024 nt
	global_load_dwordx4 v[64:67], v[50:51], off nt
	s_andn2_b64 vcc, exec, s[8:9]
	s_waitcnt vmcnt(7)
	v_lshlrev_b32_e32 v68, 16, v40
	v_and_b32_e32 v69, 0xffff0000, v40
	v_lshlrev_b32_e32 v40, 16, v41
	v_and_b32_e32 v41, 0xffff0000, v41
	s_waitcnt vmcnt(6)
	v_lshlrev_b32_e32 v71, 16, v43
	v_lshlrev_b32_e32 v70, 16, v42
	v_and_b32_e32 v43, 0xffff0000, v43
	v_and_b32_e32 v42, 0xffff0000, v42
	s_waitcnt vmcnt(5)
	v_and_b32_e32 v73, 0xffff0000, v44
	s_waitcnt vmcnt(4)
	v_lshlrev_b32_e32 v75, 16, v46
	v_and_b32_e32 v77, 0xffff0000, v46
	v_mul_f32_e32 v74, v41, v41
	v_mul_f32_e32 v76, v69, v69
	v_lshlrev_b32_e32 v72, 16, v44
	v_lshlrev_b32_e32 v44, 16, v45
	v_and_b32_e32 v45, 0xffff0000, v45
	v_pk_mul_f32 v[78:79], v[42:43], v[42:43]
	v_mov_b32_e32 v81, v75
	v_mul_f32_e32 v80, v73, v73
	v_pk_fma_f32 v[84:85], v[40:41], v[40:41], v[74:75] op_sel_hi:[1,1,0]
	v_pk_fma_f32 v[86:87], v[68:69], v[68:69], v[76:77] op_sel_hi:[1,1,0]
	v_lshlrev_b32_e32 v46, 16, v47
	v_and_b32_e32 v47, 0xffff0000, v47
	v_mul_f32_e32 v82, v45, v45
	v_pk_fma_f32 v[78:79], v[70:71], v[70:71], v[78:79]
	v_pk_fma_f32 v[88:89], v[72:73], v[72:73], v[80:81] op_sel_hi:[1,1,0]
	v_mov_b32_e32 v74, v86
	v_mov_b32_e32 v80, v84
	v_mul_f32_e32 v90, v77, v77
	v_mul_f32_e32 v91, v46, v46
	v_mul_f32_e32 v92, v47, v47
	v_pk_fma_f32 v[82:83], v[44:45], v[44:45], v[82:83] op_sel_hi:[1,1,0]
	v_pk_add_f32 v[84:85], v[86:87], v[84:85]
	v_pk_add_f32 v[78:79], v[78:79], v[78:79] op_sel:[0,1] op_sel_hi:[1,0]
	v_pk_mul_f32 v[80:81], v[74:75], v[80:81]
	v_mov_b32_e32 v89, v91
	v_mov_b32_e32 v83, v92
	v_mov_b32_e32 v79, v90
	v_mov_b32_e32 v85, v81
	v_pk_add_f32 v[82:83], v[88:89], v[82:83]
	v_pk_add_f32 v[78:79], v[84:85], v[78:79]
	s_nop 0
	v_pk_add_f32 v[78:79], v[78:79], v[82:83]
	s_nop 0
	v_add_f32_e32 v74, v78, v79
	s_nop 1
	v_add_f32_dpp v74, v74, v74 quad_perm:[1,0,3,2] row_mask:0xf bank_mask:0xf bound_ctrl:1
	v_mov_b32_e32 v78, v70
	v_mov_b32_e32 v79, v42
	v_mov_b32_e32 v42, v71
	s_nop 1
	v_add_f32_dpp v74, v74, v74 quad_perm:[2,3,0,1] row_mask:0xf bank_mask:0xf bound_ctrl:1
	s_nop 1
	v_add_f32_dpp v74, v74, v74 row_half_mirror row_mask:0xf bank_mask:0xf bound_ctrl:1
	s_nop 1
	v_add_f32_dpp v74, v74, v74 row_ror:8 row_mask:0xf bank_mask:0xf bound_ctrl:1
	v_mov_b32_e32 v76, v74
	s_nop 1
	v_permlane16_swap_b32 v76, v74
	s_nop 1
	v_add_f32_e32 v74, v74, v76
	v_mov_b32_e32 v76, v74
	s_nop 1
	v_permlane32_swap_b32 v76, v74
	s_nop 1
	v_add_f32_e32 v70, v74, v76
	v_fmamk_f32 v70, v70, 0x3a800000, v59
	v_rsq_f32_e32 v70, v70
	v_mov_b32_e32 v76, v75
	v_pk_mul_f32 v[68:69], v[70:71], v[68:69] op_sel_hi:[0,1]
	v_pk_mul_f32 v[40:41], v[70:71], v[40:41] op_sel_hi:[0,1]
	v_pk_mul_f32 v[74:75], v[70:71], v[78:79] op_sel_hi:[0,1]
	v_pk_mul_f32 v[42:43], v[70:71], v[42:43] op_sel_hi:[0,1]
	v_pk_mul_f32 v[72:73], v[70:71], v[72:73] op_sel_hi:[0,1]
	v_pk_mul_f32 v[78:79], v[70:71], v[44:45] op_sel_hi:[0,1]
	v_pk_mul_f32 v[76:77], v[76:77], v[70:71] op_sel_hi:[1,0]
	v_pk_mul_f32 v[70:71], v[46:47], v[70:71] op_sel_hi:[1,0]
	s_waitcnt vmcnt(3)
	v_pk_fma_f32 v[46:47], v[2:3], v[40:41], v[34:35]
	v_pk_fma_f32 v[44:45], v[0:1], v[68:69], v[32:33]
	s_waitcnt vmcnt(2)
	v_pk_fma_f32 v[42:43], v[6:7], v[42:43], v[38:39]
	v_pk_fma_f32 v[40:41], v[4:5], v[74:75], v[36:37]
	s_waitcnt vmcnt(1)
	v_pk_fma_f32 v[38:39], v[18:19], v[78:79], v[62:63]
	v_pk_fma_f32 v[36:37], v[16:17], v[72:73], v[60:61]
	s_waitcnt vmcnt(0)
	v_pk_fma_f32 v[34:35], v[22:23], v[70:71], v[66:67]
	v_pk_fma_f32 v[32:33], v[20:21], v[76:77], v[64:65]
	s_cbranch_vccnz .LBB0_1432
	global_store_dwordx4 v[50:51], v[44:47], off offset:-3072 nt
	global_store_dwordx4 v[50:51], v[40:43], off offset:-2048 nt
	global_store_dwordx4 v[50:51], v[36:39], off offset:-1024 nt
	global_store_dwordx4 v[50:51], v[32:35], off nt
	s_branch .LBB0_1432

.LBB0_1870:
	v_pk_mul_f32 v[60:61], v[46:47], v[46:47]
	v_pk_mul_f32 v[62:63], v[44:45], v[44:45]
	s_add_i32 s10, s10, s34
	v_pk_mov_b32 v[64:65], v[62:63], v[60:61] op_sel:[1,0]
	v_mov_b32_e32 v63, v61
	v_pk_add_f32 v[60:61], v[64:65], v[62:63]
	v_pk_mul_f32 v[62:63], v[42:43], v[42:43]
	v_pk_add_f32 v[60:61], v[60:61], v[60:61] op_sel_hi:[0,1]
	v_pk_mul_f32 v[64:65], v[40:41], v[40:41]
	v_mul_f32_e32 v60, v36, v36
	v_pk_mov_b32 v[66:67], v[64:65], v[62:63] op_sel:[1,0]
	v_mov_b32_e32 v65, v63
	v_pk_add_f32 v[62:63], v[66:67], v[64:65]
	v_pk_fma_f32 v[64:65], v[36:37], v[36:37], v[60:61] op_sel_hi:[1,1,0]
	v_mul_f32_e32 v60, v38, v38
	v_pk_add_f32 v[62:63], v[62:63], v[62:63] op_sel_hi:[0,1]
	v_pk_fma_f32 v[66:67], v[38:39], v[38:39], v[60:61] op_sel_hi:[1,1,0]
	v_mul_f32_e32 v64, v32, v32
	v_mul_f32_e32 v66, v33, v33
	v_mul_f32_e32 v60, v34, v34
	v_mul_f32_e32 v62, v35, v35
	v_pk_add_f32 v[64:65], v[64:65], v[66:67]
	v_pk_add_f32 v[60:61], v[60:61], v[62:63]
	v_add_co_u32_e32 v62, vcc, s0, v48
	v_pk_add_f32 v[60:61], v[64:65], v[60:61]
	s_nop 0
	v_addc_co_u32_e32 v63, vcc, -1, v49, vcc
	v_add_f32_e32 v59, v60, v61
	s_nop 1
	v_add_f32_dpp v59, v59, v59 quad_perm:[1,0,3,2] row_mask:0xf bank_mask:0xf bound_ctrl:1
	v_lshl_add_u64 v[48:49], v[48:49], 0, s[14:15]
	s_cmp_lt_i32 s10, 0x10000
	v_lshl_add_u64 v[50:51], v[50:51], 0, s[12:13]
	s_nop 1
	v_add_f32_dpp v59, v59, v59 quad_perm:[2,3,0,1] row_mask:0xf bank_mask:0xf bound_ctrl:1
	s_nop 1
	v_add_f32_dpp v59, v59, v59 row_half_mirror row_mask:0xf bank_mask:0xf bound_ctrl:1
	s_nop 1
	v_add_f32_dpp v59, v59, v59 row_ror:8 row_mask:0xf bank_mask:0xf bound_ctrl:1
	v_mov_b32_e32 v60, v59
	s_nop 1
	v_permlane16_swap_b32 v60, v59
	s_nop 1
	v_add_f32_e32 v59, v59, v60
	v_mov_b32_e32 v60, v59
	s_nop 1
	v_permlane32_swap_b32 v60, v59
	s_nop 1
	v_add_f32_e32 v59, v59, v60
	v_fmamk_f32 v59, v59, 0x3a800000, v58
	v_rsq_f32_e32 v60, v59
	s_nop 0
	v_pk_mul_f32 v[44:45], v[44:45], v[60:61] op_sel_hi:[1,0]
	v_pk_mul_f32 v[46:47], v[46:47], v[60:61] op_sel_hi:[1,0]
	v_pk_mul_f32 v[40:41], v[40:41], v[60:61] op_sel_hi:[1,0]
	v_pk_mul_f32 v[42:43], v[42:43], v[60:61] op_sel_hi:[1,0]
	v_pk_mul_f32 v[36:37], v[36:37], v[60:61] op_sel_hi:[1,0]
	v_pk_mul_f32 v[38:39], v[38:39], v[60:61] op_sel_hi:[1,0]
	v_pk_mul_f32 v[32:33], v[32:33], v[60:61] op_sel_hi:[1,0]
	v_pk_mul_f32 v[34:35], v[34:35], v[60:61] op_sel_hi:[1,0]
	v_pk_mul_f32 v[46:47], v[6:7], v[46:47]
	v_pk_mul_f32 v[44:45], v[4:5], v[44:45]
	v_pk_mul_f32 v[42:43], v[18:19], v[42:43]
	v_pk_mul_f32 v[40:41], v[16:17], v[40:41]
	v_pk_mul_f32 v[38:39], v[22:23], v[38:39]
	v_pk_mul_f32 v[36:37], v[20:21], v[36:37]
	v_pk_mul_f32 v[34:35], v[30:31], v[34:35]
	v_pk_mul_f32 v[32:33], v[28:29], v[32:33]
	v_cvt_pk_bf16_f32 v44, v44, v45
	v_cvt_pk_bf16_f32 v45, v46, v47
	v_cvt_pk_bf16_f32 v40, v40, v41
	v_cvt_pk_bf16_f32 v41, v42, v43
	v_cvt_pk_bf16_f32 v36, v36, v37
	v_cvt_pk_bf16_f32 v37, v38, v39
	v_cvt_pk_bf16_f32 v32, v32, v33
	v_cvt_pk_bf16_f32 v33, v34, v35
	global_store_dwordx2 v[62:63], v[44:45], off offset:-1536
	global_store_dwordx2 v[62:63], v[40:41], off offset:-1024
	global_store_dwordx2 v[62:63], v[36:37], off offset:-512
	global_store_dwordx2 v[62:63], v[32:33], off
	s_cbranch_scc0 .LBB0_1873
.LBB0_1871:
	global_load_dwordx2 v[40:41], v[48:49], off offset:-1536 nt
	global_load_dwordx2 v[42:43], v[48:49], off offset:-1024 nt
	global_load_dwordx2 v[44:45], v[48:49], off offset:-512 nt
	global_load_dwordx2 v[46:47], v[48:49], off nt
	global_load_dwordx4 v[32:35], v[50:51], off offset:-3072 nt
	global_load_dwordx4 v[36:39], v[50:51], off offset:-2048 nt
	global_load_dwordx4 v[60:63], v[50:51], off offset:-1024 nt
	global_load_dwordx4 v[64:67], v[50:51], off nt
	s_andn2_b64 vcc, exec, s[16:17]
	s_waitcnt vmcnt(7)
	v_lshlrev_b32_e32 v68, 16, v40
	v_and_b32_e32 v69, 0xffff0000, v40
	v_lshlrev_b32_e32 v40, 16, v41
	v_and_b32_e32 v41, 0xffff0000, v41
	s_waitcnt vmcnt(6)
	v_lshlrev_b32_e32 v71, 16, v43
	v_lshlrev_b32_e32 v70, 16, v42
	v_and_b32_e32 v43, 0xffff0000, v43
	v_and_b32_e32 v42, 0xffff0000, v42
	s_waitcnt vmcnt(5)
	v_and_b32_e32 v73, 0xffff0000, v44
	s_waitcnt vmcnt(4)
	v_lshlrev_b32_e32 v75, 16, v46
	v_and_b32_e32 v77, 0xffff0000, v46
	v_mul_f32_e32 v74, v41, v41
	v_mul_f32_e32 v76, v69, v69
	v_lshlrev_b32_e32 v72, 16, v44
	v_lshlrev_b32_e32 v44, 16, v45
	v_and_b32_e32 v45, 0xffff0000, v45
	v_pk_mul_f32 v[78:79], v[42:43], v[42:43]
	v_mov_b32_e32 v81, v75
	v_mul_f32_e32 v80, v73, v73
	v_pk_fma_f32 v[84:85], v[40:41], v[40:41], v[74:75] op_sel_hi:[1,1,0]
	v_pk_fma_f32 v[86:87], v[68:69], v[68:69], v[76:77] op_sel_hi:[1,1,0]
	v_lshlrev_b32_e32 v46, 16, v47
	v_and_b32_e32 v47, 0xffff0000, v47
	v_mul_f32_e32 v82, v45, v45
	v_pk_fma_f32 v[78:79], v[70:71], v[70:71], v[78:79]
	v_pk_fma_f32 v[88:89], v[72:73], v[72:73], v[80:81] op_sel_hi:[1,1,0]
	v_mov_b32_e32 v74, v86
	v_mov_b32_e32 v80, v84
	v_mul_f32_e32 v59, v77, v77
	v_mul_f32_e32 v90, v46, v46
	v_mul_f32_e32 v91, v47, v47
	v_pk_fma_f32 v[82:83], v[44:45], v[44:45], v[82:83] op_sel_hi:[1,1,0]
	v_pk_add_f32 v[84:85], v[86:87], v[84:85]
	v_pk_add_f32 v[78:79], v[78:79], v[78:79] op_sel:[0,1] op_sel_hi:[1,0]
	v_pk_mul_f32 v[80:81], v[74:75], v[80:81]
	v_mov_b32_e32 v89, v90
	v_mov_b32_e32 v83, v91
	v_mov_b32_e32 v79, v59
	v_mov_b32_e32 v85, v81
	v_pk_add_f32 v[82:83], v[88:89], v[82:83]
	v_pk_add_f32 v[78:79], v[84:85], v[78:79]
	v_mov_b32_e32 v76, v75
	v_pk_add_f32 v[78:79], v[78:79], v[82:83]
	s_nop 0
	v_add_f32_e32 v59, v78, v79
	s_nop 1
	v_add_f32_dpp v59, v59, v59 quad_perm:[1,0,3,2] row_mask:0xf bank_mask:0xf bound_ctrl:1
	v_mov_b32_e32 v78, v70
	v_mov_b32_e32 v79, v42
	v_mov_b32_e32 v42, v71
	s_nop 1
	v_add_f32_dpp v59, v59, v59 quad_perm:[2,3,0,1] row_mask:0xf bank_mask:0xf bound_ctrl:1
	s_nop 1
	v_add_f32_dpp v59, v59, v59 row_half_mirror row_mask:0xf bank_mask:0xf bound_ctrl:1
	s_nop 1
	v_add_f32_dpp v59, v59, v59 row_ror:8 row_mask:0xf bank_mask:0xf bound_ctrl:1
	v_mov_b32_e32 v74, v59
	s_nop 1
	v_permlane16_swap_b32 v74, v59
	s_nop 1
	v_add_f32_e32 v59, v59, v74
	v_mov_b32_e32 v74, v59
	s_nop 1
	v_permlane32_swap_b32 v74, v59
	s_nop 1
	v_add_f32_e32 v59, v59, v74
	v_fmamk_f32 v59, v59, 0x3a800000, v58
	v_rsq_f32_e32 v70, v59
	s_nop 0
	v_pk_mul_f32 v[68:69], v[70:71], v[68:69] op_sel_hi:[0,1]
	v_pk_mul_f32 v[40:41], v[70:71], v[40:41] op_sel_hi:[0,1]
	v_pk_mul_f32 v[74:75], v[70:71], v[78:79] op_sel_hi:[0,1]
	v_pk_mul_f32 v[42:43], v[70:71], v[42:43] op_sel_hi:[0,1]
	v_pk_mul_f32 v[72:73], v[70:71], v[72:73] op_sel_hi:[0,1]
	v_pk_mul_f32 v[78:79], v[70:71], v[44:45] op_sel_hi:[0,1]
	v_pk_mul_f32 v[76:77], v[76:77], v[70:71] op_sel_hi:[1,0]
	v_pk_mul_f32 v[70:71], v[46:47], v[70:71] op_sel_hi:[1,0]
	s_waitcnt vmcnt(3)
	v_pk_fma_f32 v[46:47], v[2:3], v[40:41], v[34:35]
	v_pk_fma_f32 v[44:45], v[0:1], v[68:69], v[32:33]
	s_waitcnt vmcnt(2)
	v_pk_fma_f32 v[42:43], v[10:11], v[42:43], v[38:39]
	v_pk_fma_f32 v[40:41], v[8:9], v[74:75], v[36:37]
	s_waitcnt vmcnt(1)
	v_pk_fma_f32 v[38:39], v[14:15], v[78:79], v[62:63]
	v_pk_fma_f32 v[36:37], v[12:13], v[72:73], v[60:61]
	s_waitcnt vmcnt(0)
	v_pk_fma_f32 v[34:35], v[26:27], v[70:71], v[66:67]
	v_pk_fma_f32 v[32:33], v[24:25], v[76:77], v[64:65]
	s_cbranch_vccnz .LBB0_1870
	global_store_dwordx4 v[50:51], v[44:47], off offset:-3072 nt
	global_store_dwordx4 v[50:51], v[40:43], off offset:-2048 nt
	global_store_dwordx4 v[50:51], v[36:39], off offset:-1024 nt
	global_store_dwordx4 v[50:51], v[32:35], off nt
	s_branch .LBB0_1870

.LBB0_2121:
	v_pk_mul_f32 v[60:61], v[46:47], v[46:47]
	v_pk_mul_f32 v[62:63], v[44:45], v[44:45]
	s_add_i32 s3, s3, s34
	v_pk_mov_b32 v[64:65], v[62:63], v[60:61] op_sel:[1,0]
	v_mov_b32_e32 v63, v61
	v_pk_add_f32 v[60:61], v[64:65], v[62:63]
	v_pk_mul_f32 v[62:63], v[42:43], v[42:43]
	v_pk_add_f32 v[60:61], v[60:61], v[60:61] op_sel_hi:[0,1]
	v_pk_mul_f32 v[64:65], v[40:41], v[40:41]
	v_mul_f32_e32 v60, v36, v36
	v_pk_mov_b32 v[66:67], v[64:65], v[62:63] op_sel:[1,0]
	v_mov_b32_e32 v65, v63
	v_pk_add_f32 v[62:63], v[66:67], v[64:65]
	v_pk_fma_f32 v[64:65], v[36:37], v[36:37], v[60:61] op_sel_hi:[1,1,0]
	v_mul_f32_e32 v60, v38, v38
	v_pk_add_f32 v[62:63], v[62:63], v[62:63] op_sel_hi:[0,1]
	v_pk_fma_f32 v[66:67], v[38:39], v[38:39], v[60:61] op_sel_hi:[1,1,0]
	v_mul_f32_e32 v64, v32, v32
	v_mul_f32_e32 v66, v33, v33
	v_mul_f32_e32 v60, v34, v34
	v_mul_f32_e32 v62, v35, v35
	v_pk_add_f32 v[64:65], v[64:65], v[66:67]
	v_pk_add_f32 v[60:61], v[60:61], v[62:63]
	v_add_co_u32_e32 v62, vcc, s1, v48
	v_pk_add_f32 v[60:61], v[64:65], v[60:61]
	s_nop 0
	v_addc_co_u32_e32 v63, vcc, -1, v49, vcc
	v_add_f32_e32 v60, v60, v61
	s_nop 1
	v_add_f32_dpp v60, v60, v60 quad_perm:[1,0,3,2] row_mask:0xf bank_mask:0xf bound_ctrl:1
	v_lshl_add_u64 v[48:49], v[48:49], 0, s[18:19]
	s_cmp_lt_i32 s3, 0x10000
	v_lshl_add_u64 v[50:51], v[50:51], 0, s[20:21]
	s_nop 1
	v_add_f32_dpp v60, v60, v60 quad_perm:[2,3,0,1] row_mask:0xf bank_mask:0xf bound_ctrl:1
	s_nop 1
	v_add_f32_dpp v60, v60, v60 row_half_mirror row_mask:0xf bank_mask:0xf bound_ctrl:1
	s_nop 1
	v_add_f32_dpp v60, v60, v60 row_ror:8 row_mask:0xf bank_mask:0xf bound_ctrl:1
	v_mov_b32_e32 v61, v60
	s_nop 1
	v_permlane16_swap_b32 v61, v60
	s_nop 1
	v_add_f32_e32 v60, v60, v61
	v_mov_b32_e32 v61, v60
	s_nop 1
	v_permlane32_swap_b32 v61, v60
	s_nop 1
	v_add_f32_e32 v60, v60, v61
	v_fmamk_f32 v60, v60, 0x3a800000, v59
	v_rsq_f32_e32 v60, v60
	s_nop 0
	v_pk_mul_f32 v[44:45], v[44:45], v[60:61] op_sel_hi:[1,0]
	v_pk_mul_f32 v[46:47], v[46:47], v[60:61] op_sel_hi:[1,0]
	v_pk_mul_f32 v[40:41], v[40:41], v[60:61] op_sel_hi:[1,0]
	v_pk_mul_f32 v[42:43], v[42:43], v[60:61] op_sel_hi:[1,0]
	v_pk_mul_f32 v[36:37], v[36:37], v[60:61] op_sel_hi:[1,0]
	v_pk_mul_f32 v[38:39], v[38:39], v[60:61] op_sel_hi:[1,0]
	v_pk_mul_f32 v[32:33], v[32:33], v[60:61] op_sel_hi:[1,0]
	v_pk_mul_f32 v[34:35], v[34:35], v[60:61] op_sel_hi:[1,0]
	v_pk_mul_f32 v[46:47], v[6:7], v[46:47]
	v_pk_mul_f32 v[44:45], v[4:5], v[44:45]
	v_pk_mul_f32 v[42:43], v[18:19], v[42:43]
	v_pk_mul_f32 v[40:41], v[16:17], v[40:41]
	v_pk_mul_f32 v[38:39], v[22:23], v[38:39]
	v_pk_mul_f32 v[36:37], v[20:21], v[36:37]
	v_pk_mul_f32 v[34:35], v[30:31], v[34:35]
	v_pk_mul_f32 v[32:33], v[28:29], v[32:33]
	v_cvt_pk_bf16_f32 v44, v44, v45
	v_cvt_pk_bf16_f32 v45, v46, v47
	v_cvt_pk_bf16_f32 v40, v40, v41
	v_cvt_pk_bf16_f32 v41, v42, v43
	v_cvt_pk_bf16_f32 v36, v36, v37
	v_cvt_pk_bf16_f32 v37, v38, v39
	v_cvt_pk_bf16_f32 v32, v32, v33
	v_cvt_pk_bf16_f32 v33, v34, v35
	global_store_dwordx2 v[62:63], v[44:45], off offset:-1536
	global_store_dwordx2 v[62:63], v[40:41], off offset:-1024
	global_store_dwordx2 v[62:63], v[36:37], off offset:-512
	global_store_dwordx2 v[62:63], v[32:33], off
	s_cbranch_scc0 .LBB0_2124
.LBB0_2122:
	global_load_dwordx2 v[40:41], v[48:49], off offset:-1536 nt
	global_load_dwordx2 v[42:43], v[48:49], off offset:-1024 nt
	global_load_dwordx2 v[44:45], v[48:49], off offset:-512 nt
	global_load_dwordx2 v[46:47], v[48:49], off nt
	global_load_dwordx4 v[32:35], v[50:51], off offset:-3072 nt
	global_load_dwordx4 v[36:39], v[50:51], off offset:-2048 nt
	global_load_dwordx4 v[60:63], v[50:51], off offset:-1024 nt
	global_load_dwordx4 v[64:67], v[50:51], off nt
	s_andn2_b64 vcc, exec, s[10:11]
	s_waitcnt vmcnt(7)
	v_lshlrev_b32_e32 v68, 16, v40
	v_and_b32_e32 v69, 0xffff0000, v40
	v_lshlrev_b32_e32 v40, 16, v41
	v_and_b32_e32 v41, 0xffff0000, v41
	s_waitcnt vmcnt(6)
	v_lshlrev_b32_e32 v71, 16, v43
	v_lshlrev_b32_e32 v70, 16, v42
	v_and_b32_e32 v43, 0xffff0000, v43
	v_and_b32_e32 v42, 0xffff0000, v42
	s_waitcnt vmcnt(5)
	v_and_b32_e32 v73, 0xffff0000, v44
	s_waitcnt vmcnt(4)
	v_lshlrev_b32_e32 v75, 16, v46
	v_and_b32_e32 v77, 0xffff0000, v46
	v_mul_f32_e32 v74, v41, v41
	v_mul_f32_e32 v76, v69, v69
	v_lshlrev_b32_e32 v72, 16, v44
	v_lshlrev_b32_e32 v44, 16, v45
	v_and_b32_e32 v45, 0xffff0000, v45
	v_pk_mul_f32 v[78:79], v[42:43], v[42:43]
	v_mov_b32_e32 v81, v75
	v_mul_f32_e32 v80, v73, v73
	v_pk_fma_f32 v[84:85], v[40:41], v[40:41], v[74:75] op_sel_hi:[1,1,0]
	v_pk_fma_f32 v[86:87], v[68:69], v[68:69], v[76:77] op_sel_hi:[1,1,0]
	v_lshlrev_b32_e32 v46, 16, v47
	v_and_b32_e32 v47, 0xffff0000, v47
	v_mul_f32_e32 v82, v45, v45
	v_pk_fma_f32 v[78:79], v[70:71], v[70:71], v[78:79]
	v_pk_fma_f32 v[88:89], v[72:73], v[72:73], v[80:81] op_sel_hi:[1,1,0]
	v_mov_b32_e32 v74, v86
	v_mov_b32_e32 v80, v84
	v_mul_f32_e32 v90, v77, v77
	v_mul_f32_e32 v91, v46, v46
	v_mul_f32_e32 v92, v47, v47
	v_pk_fma_f32 v[82:83], v[44:45], v[44:45], v[82:83] op_sel_hi:[1,1,0]
	v_pk_add_f32 v[84:85], v[86:87], v[84:85]
	v_pk_add_f32 v[78:79], v[78:79], v[78:79] op_sel:[0,1] op_sel_hi:[1,0]
	v_pk_mul_f32 v[80:81], v[74:75], v[80:81]
	v_mov_b32_e32 v89, v91
	v_mov_b32_e32 v83, v92
	v_mov_b32_e32 v79, v90
	v_mov_b32_e32 v85, v81
	v_pk_add_f32 v[82:83], v[88:89], v[82:83]
	v_pk_add_f32 v[78:79], v[84:85], v[78:79]
	s_nop 0
	v_pk_add_f32 v[78:79], v[78:79], v[82:83]
	s_nop 0
	v_add_f32_e32 v74, v78, v79
	s_nop 1
	v_add_f32_dpp v74, v74, v74 quad_perm:[1,0,3,2] row_mask:0xf bank_mask:0xf bound_ctrl:1
	v_mov_b32_e32 v78, v70
	v_mov_b32_e32 v79, v42
	v_mov_b32_e32 v42, v71
	s_nop 1
	v_add_f32_dpp v74, v74, v74 quad_perm:[2,3,0,1] row_mask:0xf bank_mask:0xf bound_ctrl:1
	s_nop 1
	v_add_f32_dpp v74, v74, v74 row_half_mirror row_mask:0xf bank_mask:0xf bound_ctrl:1
	s_nop 1
	v_add_f32_dpp v74, v74, v74 row_ror:8 row_mask:0xf bank_mask:0xf bound_ctrl:1
	v_mov_b32_e32 v76, v74
	s_nop 1
	v_permlane16_swap_b32 v76, v74
	s_nop 1
	v_add_f32_e32 v74, v74, v76
	v_mov_b32_e32 v76, v74
	s_nop 1
	v_permlane32_swap_b32 v76, v74
	s_nop 1
	v_add_f32_e32 v70, v74, v76
	v_fmamk_f32 v70, v70, 0x3a800000, v59
	v_rsq_f32_e32 v70, v70
	v_mov_b32_e32 v76, v75
	v_pk_mul_f32 v[68:69], v[70:71], v[68:69] op_sel_hi:[0,1]
	v_pk_mul_f32 v[40:41], v[70:71], v[40:41] op_sel_hi:[0,1]
	v_pk_mul_f32 v[74:75], v[70:71], v[78:79] op_sel_hi:[0,1]
	v_pk_mul_f32 v[42:43], v[70:71], v[42:43] op_sel_hi:[0,1]
	v_pk_mul_f32 v[72:73], v[70:71], v[72:73] op_sel_hi:[0,1]
	v_pk_mul_f32 v[78:79], v[70:71], v[44:45] op_sel_hi:[0,1]
	v_pk_mul_f32 v[76:77], v[76:77], v[70:71] op_sel_hi:[1,0]
	v_pk_mul_f32 v[70:71], v[46:47], v[70:71] op_sel_hi:[1,0]
	s_waitcnt vmcnt(3)
	v_pk_fma_f32 v[46:47], v[2:3], v[40:41], v[34:35]
	v_pk_fma_f32 v[44:45], v[0:1], v[68:69], v[32:33]
	s_waitcnt vmcnt(2)
	v_pk_fma_f32 v[42:43], v[10:11], v[42:43], v[38:39]
	v_pk_fma_f32 v[40:41], v[8:9], v[74:75], v[36:37]
	s_waitcnt vmcnt(1)
	v_pk_fma_f32 v[38:39], v[14:15], v[78:79], v[62:63]
	v_pk_fma_f32 v[36:37], v[12:13], v[72:73], v[60:61]
	s_waitcnt vmcnt(0)
	v_pk_fma_f32 v[34:35], v[26:27], v[70:71], v[66:67]
	v_pk_fma_f32 v[32:33], v[24:25], v[76:77], v[64:65]
	s_cbranch_vccnz .LBB0_2121
	global_store_dwordx4 v[50:51], v[44:47], off offset:-3072 nt
	global_store_dwordx4 v[50:51], v[40:43], off offset:-2048 nt
	global_store_dwordx4 v[50:51], v[36:39], off offset:-1024 nt
	global_store_dwordx4 v[50:51], v[32:35], off nt
	s_branch .LBB0_2121

.LBB0_3971:
	v_pk_mul_f32 v[60:61], v[46:47], v[46:47]
	v_pk_mul_f32 v[62:63], v[44:45], v[44:45]
	s_add_i32 s12, s12, s34
	v_pk_mov_b32 v[64:65], v[62:63], v[60:61] op_sel:[1,0]
	v_mov_b32_e32 v63, v61
	v_pk_add_f32 v[60:61], v[64:65], v[62:63]
	v_pk_mul_f32 v[62:63], v[42:43], v[42:43]
	v_pk_add_f32 v[60:61], v[60:61], v[60:61] op_sel_hi:[0,1]
	v_pk_mul_f32 v[64:65], v[40:41], v[40:41]
	v_mul_f32_e32 v60, v36, v36
	v_pk_mov_b32 v[66:67], v[64:65], v[62:63] op_sel:[1,0]
	v_mov_b32_e32 v65, v63
	v_pk_add_f32 v[62:63], v[66:67], v[64:65]
	v_pk_fma_f32 v[64:65], v[36:37], v[36:37], v[60:61] op_sel_hi:[1,1,0]
	v_mul_f32_e32 v60, v38, v38
	v_pk_add_f32 v[62:63], v[62:63], v[62:63] op_sel_hi:[0,1]
	v_pk_fma_f32 v[66:67], v[38:39], v[38:39], v[60:61] op_sel_hi:[1,1,0]
	v_mul_f32_e32 v64, v32, v32
	v_mul_f32_e32 v66, v33, v33
	v_mul_f32_e32 v60, v34, v34
	v_mul_f32_e32 v62, v35, v35
	v_pk_add_f32 v[64:65], v[64:65], v[66:67]
	v_pk_add_f32 v[60:61], v[60:61], v[62:63]
	v_add_co_u32_e32 v62, vcc, s0, v48
	v_pk_add_f32 v[60:61], v[64:65], v[60:61]
	s_nop 0
	v_addc_co_u32_e32 v63, vcc, -1, v49, vcc
	v_add_f32_e32 v59, v60, v61
	s_nop 1
	v_add_f32_dpp v59, v59, v59 quad_perm:[1,0,3,2] row_mask:0xf bank_mask:0xf bound_ctrl:1
	v_lshl_add_u64 v[48:49], v[48:49], 0, s[10:11]
	s_cmp_lt_i32 s12, 0x10000
	v_lshl_add_u64 v[50:51], v[50:51], 0, s[8:9]
	s_nop 1
	v_add_f32_dpp v59, v59, v59 quad_perm:[2,3,0,1] row_mask:0xf bank_mask:0xf bound_ctrl:1
	s_nop 1
	v_add_f32_dpp v59, v59, v59 row_half_mirror row_mask:0xf bank_mask:0xf bound_ctrl:1
	s_nop 1
	v_add_f32_dpp v59, v59, v59 row_ror:8 row_mask:0xf bank_mask:0xf bound_ctrl:1
	v_mov_b32_e32 v60, v59
	s_nop 1
	v_permlane16_swap_b32 v60, v59
	s_nop 1
	v_add_f32_e32 v59, v59, v60
	v_mov_b32_e32 v60, v59
	s_nop 1
	v_permlane32_swap_b32 v60, v59
	s_nop 1
	v_add_f32_e32 v59, v59, v60
	v_fmamk_f32 v59, v59, 0x3a800000, v58
	v_rsq_f32_e32 v60, v59
	s_nop 0
	v_pk_mul_f32 v[44:45], v[44:45], v[60:61] op_sel_hi:[1,0]
	v_pk_mul_f32 v[46:47], v[46:47], v[60:61] op_sel_hi:[1,0]
	v_pk_mul_f32 v[40:41], v[40:41], v[60:61] op_sel_hi:[1,0]
	v_pk_mul_f32 v[42:43], v[42:43], v[60:61] op_sel_hi:[1,0]
	v_pk_mul_f32 v[36:37], v[36:37], v[60:61] op_sel_hi:[1,0]
	v_pk_mul_f32 v[38:39], v[38:39], v[60:61] op_sel_hi:[1,0]
	v_pk_mul_f32 v[32:33], v[32:33], v[60:61] op_sel_hi:[1,0]
	v_pk_mul_f32 v[34:35], v[34:35], v[60:61] op_sel_hi:[1,0]
	v_pk_mul_f32 v[46:47], v[6:7], v[46:47]
	v_pk_mul_f32 v[44:45], v[4:5], v[44:45]
	v_pk_mul_f32 v[42:43], v[18:19], v[42:43]
	v_pk_mul_f32 v[40:41], v[16:17], v[40:41]
	v_pk_mul_f32 v[38:39], v[22:23], v[38:39]
	v_pk_mul_f32 v[36:37], v[20:21], v[36:37]
	v_pk_mul_f32 v[34:35], v[30:31], v[34:35]
	v_pk_mul_f32 v[32:33], v[28:29], v[32:33]
	v_cvt_pk_bf16_f32 v44, v44, v45
	v_cvt_pk_bf16_f32 v45, v46, v47
	v_cvt_pk_bf16_f32 v40, v40, v41
	v_cvt_pk_bf16_f32 v41, v42, v43
	v_cvt_pk_bf16_f32 v36, v36, v37
	v_cvt_pk_bf16_f32 v37, v38, v39
	v_cvt_pk_bf16_f32 v32, v32, v33
	v_cvt_pk_bf16_f32 v33, v34, v35
	global_store_dwordx2 v[62:63], v[44:45], off offset:-1536
	global_store_dwordx2 v[62:63], v[40:41], off offset:-1024
	global_store_dwordx2 v[62:63], v[36:37], off offset:-512
	global_store_dwordx2 v[62:63], v[32:33], off
	s_cbranch_scc0 .LBB0_3974
.LBB0_3972:
	global_load_dwordx2 v[40:41], v[48:49], off offset:-1536 nt
	global_load_dwordx2 v[42:43], v[48:49], off offset:-1024 nt
	global_load_dwordx2 v[44:45], v[48:49], off offset:-512 nt
	global_load_dwordx2 v[46:47], v[48:49], off nt
	global_load_dwordx4 v[32:35], v[50:51], off offset:-3072 nt
	global_load_dwordx4 v[36:39], v[50:51], off offset:-2048 nt
	global_load_dwordx4 v[60:63], v[50:51], off offset:-1024 nt
	global_load_dwordx4 v[64:67], v[50:51], off nt
	s_andn2_b64 vcc, exec, s[14:15]
	s_waitcnt vmcnt(7)
	v_lshlrev_b32_e32 v68, 16, v40
	v_and_b32_e32 v69, 0xffff0000, v40
	v_lshlrev_b32_e32 v40, 16, v41
	v_and_b32_e32 v41, 0xffff0000, v41
	s_waitcnt vmcnt(6)
	v_lshlrev_b32_e32 v71, 16, v43
	v_lshlrev_b32_e32 v70, 16, v42
	v_and_b32_e32 v43, 0xffff0000, v43
	v_and_b32_e32 v42, 0xffff0000, v42
	s_waitcnt vmcnt(5)
	v_and_b32_e32 v73, 0xffff0000, v44
	s_waitcnt vmcnt(4)
	v_lshlrev_b32_e32 v75, 16, v46
	v_and_b32_e32 v77, 0xffff0000, v46
	v_mul_f32_e32 v74, v41, v41
	v_mul_f32_e32 v76, v69, v69
	v_lshlrev_b32_e32 v72, 16, v44
	v_lshlrev_b32_e32 v44, 16, v45
	v_and_b32_e32 v45, 0xffff0000, v45
	v_pk_mul_f32 v[78:79], v[42:43], v[42:43]
	v_mov_b32_e32 v81, v75
	v_mul_f32_e32 v80, v73, v73
	v_pk_fma_f32 v[84:85], v[40:41], v[40:41], v[74:75] op_sel_hi:[1,1,0]
	v_pk_fma_f32 v[86:87], v[68:69], v[68:69], v[76:77] op_sel_hi:[1,1,0]
	v_lshlrev_b32_e32 v46, 16, v47
	v_and_b32_e32 v47, 0xffff0000, v47
	v_mul_f32_e32 v82, v45, v45
	v_pk_fma_f32 v[78:79], v[70:71], v[70:71], v[78:79]
	v_pk_fma_f32 v[88:89], v[72:73], v[72:73], v[80:81] op_sel_hi:[1,1,0]
	v_mov_b32_e32 v74, v86
	v_mov_b32_e32 v80, v84
	v_mul_f32_e32 v59, v77, v77
	v_mul_f32_e32 v90, v46, v46
	v_mul_f32_e32 v91, v47, v47
	v_pk_fma_f32 v[82:83], v[44:45], v[44:45], v[82:83] op_sel_hi:[1,1,0]
	v_pk_add_f32 v[84:85], v[86:87], v[84:85]
	v_pk_add_f32 v[78:79], v[78:79], v[78:79] op_sel:[0,1] op_sel_hi:[1,0]
	v_pk_mul_f32 v[80:81], v[74:75], v[80:81]
	v_mov_b32_e32 v89, v90
	v_mov_b32_e32 v83, v91
	v_mov_b32_e32 v79, v59
	v_mov_b32_e32 v85, v81
	v_pk_add_f32 v[82:83], v[88:89], v[82:83]
	v_pk_add_f32 v[78:79], v[84:85], v[78:79]
	v_mov_b32_e32 v76, v75
	v_pk_add_f32 v[78:79], v[78:79], v[82:83]
	s_nop 0
	v_add_f32_e32 v59, v78, v79
	s_nop 1
	v_add_f32_dpp v59, v59, v59 quad_perm:[1,0,3,2] row_mask:0xf bank_mask:0xf bound_ctrl:1
	v_mov_b32_e32 v78, v70
	v_mov_b32_e32 v79, v42
	v_mov_b32_e32 v42, v71
	s_nop 1
	v_add_f32_dpp v59, v59, v59 quad_perm:[2,3,0,1] row_mask:0xf bank_mask:0xf bound_ctrl:1
	s_nop 1
	v_add_f32_dpp v59, v59, v59 row_half_mirror row_mask:0xf bank_mask:0xf bound_ctrl:1
	s_nop 1
	v_add_f32_dpp v59, v59, v59 row_ror:8 row_mask:0xf bank_mask:0xf bound_ctrl:1
	v_mov_b32_e32 v74, v59
	s_nop 1
	v_permlane16_swap_b32 v74, v59
	s_nop 1
	v_add_f32_e32 v59, v59, v74
	v_mov_b32_e32 v74, v59
	s_nop 1
	v_permlane32_swap_b32 v74, v59
	s_nop 1
	v_add_f32_e32 v59, v59, v74
	v_fmamk_f32 v59, v59, 0x3a800000, v58
	v_rsq_f32_e32 v70, v59
	s_nop 0
	v_pk_mul_f32 v[68:69], v[70:71], v[68:69] op_sel_hi:[0,1]
	v_pk_mul_f32 v[40:41], v[70:71], v[40:41] op_sel_hi:[0,1]
	v_pk_mul_f32 v[74:75], v[70:71], v[78:79] op_sel_hi:[0,1]
	v_pk_mul_f32 v[42:43], v[70:71], v[42:43] op_sel_hi:[0,1]
	v_pk_mul_f32 v[72:73], v[70:71], v[72:73] op_sel_hi:[0,1]
	v_pk_mul_f32 v[78:79], v[70:71], v[44:45] op_sel_hi:[0,1]
	v_pk_mul_f32 v[76:77], v[76:77], v[70:71] op_sel_hi:[1,0]
	v_pk_mul_f32 v[70:71], v[46:47], v[70:71] op_sel_hi:[1,0]
	s_waitcnt vmcnt(3)
	v_pk_fma_f32 v[46:47], v[2:3], v[40:41], v[34:35]
	v_pk_fma_f32 v[44:45], v[0:1], v[68:69], v[32:33]
	s_waitcnt vmcnt(2)
	v_pk_fma_f32 v[42:43], v[10:11], v[42:43], v[38:39]
	v_pk_fma_f32 v[40:41], v[8:9], v[74:75], v[36:37]
	s_waitcnt vmcnt(1)
	v_pk_fma_f32 v[38:39], v[14:15], v[78:79], v[62:63]
	v_pk_fma_f32 v[36:37], v[12:13], v[72:73], v[60:61]
	s_waitcnt vmcnt(0)
	v_pk_fma_f32 v[34:35], v[26:27], v[70:71], v[66:67]
	v_pk_fma_f32 v[32:33], v[24:25], v[76:77], v[64:65]
	s_cbranch_vccnz .LBB0_3971
	global_store_dwordx4 v[50:51], v[44:47], off offset:-3072 nt
	global_store_dwordx4 v[50:51], v[40:43], off offset:-2048 nt
	global_store_dwordx4 v[50:51], v[36:39], off offset:-1024 nt
	global_store_dwordx4 v[50:51], v[32:35], off nt
	s_branch .LBB0_3971

.LBB0_4223:
	global_load_dwordx2 v[20:21], v[16:17], off offset:-1536 nt
	global_load_dwordx2 v[26:27], v[16:17], off offset:-1024 nt
	global_load_dwordx2 v[30:31], v[16:17], off offset:-512 nt
	global_load_dwordx2 v[34:35], v[16:17], off nt
	s_and_b64 vcc, exec, s[0:1]
	s_waitcnt vmcnt(3)
	v_lshlrev_b32_e32 v22, 16, v20
	v_and_b32_e32 v23, 0xffff0000, v20
	v_lshlrev_b32_e32 v20, 16, v21
	v_and_b32_e32 v21, 0xffff0000, v21
	s_waitcnt vmcnt(2)
	v_lshlrev_b32_e32 v24, 16, v26
	v_and_b32_e32 v25, 0xffff0000, v26
	v_lshlrev_b32_e32 v26, 16, v27
	v_and_b32_e32 v27, 0xffff0000, v27
	s_waitcnt vmcnt(1)
	v_lshlrev_b32_e32 v28, 16, v30
	v_and_b32_e32 v29, 0xffff0000, v30
	v_lshlrev_b32_e32 v30, 16, v31
	v_and_b32_e32 v31, 0xffff0000, v31
	v_mul_f32_e32 v43, v23, v23
	s_waitcnt lgkmcnt(0)
	v_mul_f32_e32 v44, v21, v21
	v_mul_f32_e32 v45, v25, v25
	v_mul_f32_e32 v46, v27, v27
	s_waitcnt vmcnt(0)
	v_lshlrev_b32_e32 v32, 16, v34
	v_and_b32_e32 v33, 0xffff0000, v34
	v_lshlrev_b32_e32 v34, 16, v35
	v_and_b32_e32 v35, 0xffff0000, v35
	v_mul_f32_e32 v47, v29, v29
	v_mul_f32_e32 v48, v31, v31
	v_fmac_f32_e32 v43, v22, v22
	v_fmac_f32_e32 v44, v20, v20
	v_fmac_f32_e32 v45, v24, v24
	v_fmac_f32_e32 v46, v26, v26
	v_mul_f32_e32 v49, v33, v33
	v_mul_f32_e32 v50, v35, v35
	v_fmac_f32_e32 v47, v28, v28
	v_fmac_f32_e32 v48, v30, v30
	v_add_f32_e32 v43, v43, v44
	v_add_f32_e32 v44, v45, v46
	v_fmac_f32_e32 v49, v32, v32
	v_fmac_f32_e32 v50, v34, v34
	v_add_f32_e32 v45, v47, v48
	v_add_f32_e32 v43, v43, v44
	v_add_f32_e32 v43, v43, v45
	v_add_f32_e32 v44, v49, v50
	v_add_f32_e32 v43, v43, v44
	s_nop 1
	v_add_f32_dpp v43, v43, v43 quad_perm:[1,0,3,2] row_mask:0xf bank_mask:0xf bound_ctrl:1
	s_nop 1
	v_add_f32_dpp v43, v43, v43 quad_perm:[2,3,0,1] row_mask:0xf bank_mask:0xf bound_ctrl:1
	s_nop 1
	v_add_f32_dpp v43, v43, v43 row_half_mirror row_mask:0xf bank_mask:0xf bound_ctrl:1
	s_nop 1
	v_add_f32_dpp v43, v43, v43 row_ror:8 row_mask:0xf bank_mask:0xf bound_ctrl:1
	v_mov_b32_e32 v44, v43
	s_nop 1
	v_permlane16_swap_b32 v44, v43
	s_nop 1
	v_add_f32_e32 v43, v43, v44
	v_mov_b32_e32 v44, v43
	s_nop 1
	v_permlane32_swap_b32 v44, v43
	s_nop 1
	v_add_f32_e32 v43, v43, v44
	s_cbranch_vccnz .LBB0_4222
	global_load_dwordx4 v[46:49], v[18:19], off nt
	global_load_dwordx4 v[50:53], v[18:19], off offset:-1024 nt
	global_load_dwordx4 v[54:57], v[18:19], off offset:-2048 nt
	global_load_dwordx4 v[58:61], v[18:19], off offset:-3072 nt
	v_fmamk_f32 v43, v43, 0x3a800000, v42
	v_rsq_f32_e32 v44, v43
	s_nop 0
	v_pk_mul_f32 v[32:33], v[32:33], v[44:45] op_sel_hi:[1,0]
	v_pk_mul_f32 v[34:35], v[34:35], v[44:45] op_sel_hi:[1,0]
	v_pk_mul_f32 v[28:29], v[28:29], v[44:45] op_sel_hi:[1,0]
	v_pk_mul_f32 v[30:31], v[30:31], v[44:45] op_sel_hi:[1,0]
	v_pk_mul_f32 v[62:63], v[24:25], v[44:45] op_sel_hi:[1,0]
	v_pk_mul_f32 v[64:65], v[26:27], v[44:45] op_sel_hi:[1,0]
	v_pk_mul_f32 v[66:67], v[22:23], v[44:45] op_sel_hi:[1,0]
	v_pk_mul_f32 v[44:45], v[20:21], v[44:45] op_sel_hi:[1,0]
	s_waitcnt vmcnt(3)
	v_pk_fma_f32 v[22:23], v[14:15], v[34:35], v[48:49]
	v_pk_fma_f32 v[20:21], v[12:13], v[32:33], v[46:47]
	s_waitcnt vmcnt(2)
	v_pk_fma_f32 v[26:27], v[6:7], v[30:31], v[52:53]
	s_waitcnt vmcnt(0)
	v_pk_fma_f32 v[34:35], v[10:11], v[44:45], v[60:61]
	v_pk_fma_f32 v[32:33], v[8:9], v[66:67], v[58:59]
	v_pk_fma_f32 v[24:25], v[4:5], v[28:29], v[50:51]
	v_pk_fma_f32 v[30:31], v[2:3], v[64:65], v[56:57]
	v_pk_fma_f32 v[28:29], v[0:1], v[62:63], v[54:55]
	global_store_dwordx4 v[18:19], v[32:35], off offset:-3072 nt
	global_store_dwordx4 v[18:19], v[28:31], off offset:-2048 nt
	global_store_dwordx4 v[18:19], v[24:27], off offset:-1024 nt
	global_store_dwordx4 v[18:19], v[20:23], off nt
	s_branch .LBB0_4222
